# weight-conversion f32 loads non-temporal during L0 recurrence
# speedup vs baseline: 1.0064x; 1.0064x over previous
; #define LAS __attribute__((address_space(3)))
; __device__ __forceinline__ unsigned pk2(float lo, float hi) { f32x2_t v = {lo, hi}; bf16x2_t b = __builtin_convertvector(v, bf16x2_t); return __builtin_bit_cast(unsigned, b); }
; __device__ __forceinline__ void transpose_item(const float* W, int K, int N, bf16* WT, const float* scale, LAS float* scr, int item, int lane) {
;     ...
;         const int q = lane & 7, r = lane >> 3;
;         f32x4 v[8];
; #pragma unroll
;         for (int i = 0; i < 8; ++i) v[i] = *(const f32x4*)(W + (size_t)(k0 + 8 * i + r) * N + n0 + 4 * q);
; #pragma unroll
;         for (int i = 0; i < 8; ++i) { const int kk = 8 * i + r; f32x4 x = v[i]; if (scale) x = x * scale[k0 + kk];
;             scr[kk * 33 + 4 * q + 0] = x[0]; scr[kk * 33 + 4 * q + 1] = x[1]; scr[kk * 33 + 4 * q + 2] = x[2]; scr[kk * 33 + 4 * q + 3] = x[3]; }
;     }
;     asm volatile("s_waitcnt lgkmcnt(0)" ::: "memory");
;     const int c = lane & 7;
; #pragma unroll
;     for (int j = 0; j < 4; ++j) { const int n = (lane >> 3) + 8 * j; const LAS float* s = scr + (8 * c) * 33 + n;
;         v4u o; o.x = pk2(s[0 * 33], s[1 * 33]); o.y = pk2(s[2 * 33], s[3 * 33]); o.z = pk2(s[4 * 33], s[5 * 33]); o.w = pk2(s[6 * 33], s[7 * 33]);
;         *(v4u*)(WT + (size_t)(n0 + n) * K + k0 + 8 * c) = o; }
;     asm volatile("s_waitcnt lgkmcnt(0)" ::: "memory");
.LBB0_1263:
	s_mul_hi_i32 s0, s6, 0x66666667
	s_lshr_b32 s1, s0, 31
	s_ashr_i32 s0, s0, 7
	s_add_i32 s0, s0, s1
	s_lshl_b32 s2, s0, 6
	s_mulk_i32 s0, 0xd800
	s_add_i32 s0, s4, s0
	s_ashr_i32 s1, s0, 31
	s_waitcnt vmcnt(1)
	v_or_b32_e32 v48, s2, v1
	v_lshl_add_u64 v[2:3], s[0:1], 2, v[22:23]
	v_mad_i64_i32 v[4:5], s[8:9], v48, s12, v[2:3]
	global_load_dwordx4 v[36:39], v[4:5], off nt
	v_or_b32_e32 v4, 8, v48
	v_mad_i64_i32 v[4:5], s[8:9], v4, s12, v[2:3]
	global_load_dwordx4 v[40:43], v[4:5], off nt
	v_or_b32_e32 v4, 16, v48
	v_mad_i64_i32 v[4:5], s[8:9], v4, s12, v[2:3]
	global_load_dwordx4 v[44:47], v[4:5], off nt
	v_or_b32_e32 v4, 24, v48
	v_mad_i64_i32 v[4:5], s[8:9], v4, s12, v[2:3]
	global_load_dwordx4 v[18:21], v[4:5], off nt
	v_or_b32_e32 v4, 32, v48
	v_mad_i64_i32 v[4:5], s[8:9], v4, s12, v[2:3]
	global_load_dwordx4 v[14:17], v[4:5], off nt
	v_or_b32_e32 v4, 40, v48
	v_mad_i64_i32 v[4:5], s[8:9], v4, s12, v[2:3]
	global_load_dwordx4 v[10:13], v[4:5], off nt
	v_or_b32_e32 v4, 48, v48
	v_ashrrev_i32_e32 v49, 31, v48
	v_mad_i64_i32 v[4:5], s[8:9], v4, s12, v[2:3]
	global_load_dwordx4 v[6:9], v[4:5], off nt
	v_or_b32_e32 v4, 56, v48
	v_lshl_add_u64 v[48:49], v[48:49], 2, s[10:11]
	global_load_dword v48, v[48:49], off
	v_mad_i64_i32 v[2:3], s[8:9], v4, s12, v[2:3]
	global_load_dwordx4 v[2:5], v[2:3], off nt
	v_add_u32_e32 v35, 0x420, v34
	s_ashr_i32 s3, s2, 31
	s_add_i32 s6, s6, s7
	s_add_i32 s4, s4, s5
	s_cmpk_lt_i32 s6, 0x1400
	s_waitcnt vmcnt(1)
	v_pk_mul_f32 v[36:37], v[36:37], v[48:49] op_sel_hi:[1,0]
	v_pk_mul_f32 v[38:39], v[38:39], v[48:49] op_sel_hi:[1,0]
	ds_write2_b32 v34, v36, v37 offset1:1
	ds_write2_b32 v34, v38, v39 offset0:2 offset1:3
	v_or_b32_e32 v36, s2, v26
	v_ashrrev_i32_e32 v37, 31, v36
	v_lshl_add_u64 v[36:37], v[36:37], 2, s[10:11]
	global_load_dword v36, v[36:37], off
	s_waitcnt vmcnt(0)
	v_pk_mul_f32 v[38:39], v[42:43], v[36:37] op_sel_hi:[1,0]
	v_pk_mul_f32 v[36:37], v[40:41], v[36:37] op_sel_hi:[1,0]
	ds_write2_b32 v35, v36, v37 offset1:1
	v_or_b32_e32 v36, s2, v27
	v_ashrrev_i32_e32 v37, 31, v36
	v_lshl_add_u64 v[36:37], v[36:37], 2, s[10:11]
	global_load_dword v36, v[36:37], off
	v_add_u32_e32 v35, 0x428, v34
	ds_write2_b32 v35, v38, v39 offset1:1
	v_add_u32_e32 v35, 0x840, v34
	s_waitcnt vmcnt(0)
	v_pk_mul_f32 v[38:39], v[46:47], v[36:37] op_sel_hi:[1,0]
	v_pk_mul_f32 v[36:37], v[44:45], v[36:37] op_sel_hi:[1,0]
	ds_write2_b32 v35, v36, v37 offset1:1
	v_or_b32_e32 v36, s2, v28
	v_ashrrev_i32_e32 v37, 31, v36
	v_lshl_add_u64 v[36:37], v[36:37], 2, s[10:11]
	global_load_dword v36, v[36:37], off
	v_add_u32_e32 v35, 0x848, v34
	ds_write2_b32 v35, v38, v39 offset1:1
	v_add_u32_e32 v35, 0xc60, v34
	v_add_u32_e32 v38, s0, v1
	v_ashrrev_i32_e32 v39, 31, v38
	v_lshlrev_b64 v[40:41], 11, v[38:39]
	s_waitcnt vmcnt(0)
	v_pk_mul_f32 v[18:19], v[18:19], v[36:37] op_sel_hi:[1,0]
	v_pk_mul_f32 v[20:21], v[20:21], v[36:37] op_sel_hi:[1,0]
	ds_write2_b32 v35, v18, v19 offset1:1
	v_add_u32_e32 v18, 0xc68, v34
	ds_write2_b32 v18, v20, v21 offset1:1
	v_or_b32_e32 v18, s2, v29
	v_ashrrev_i32_e32 v19, 31, v18
	v_lshl_add_u64 v[18:19], v[18:19], 2, s[10:11]
	global_load_dword v18, v[18:19], off
	s_waitcnt vmcnt(0)
	v_pk_mul_f32 v[16:17], v[16:17], v[18:19] op_sel_hi:[1,0]
	v_pk_mul_f32 v[14:15], v[14:15], v[18:19] op_sel_hi:[1,0]
	v_add_u32_e32 v18, 0x1080, v34
	ds_write2_b32 v18, v14, v15 offset1:1
	v_add_u32_e32 v14, 0x1088, v34
	ds_write2_b32 v14, v16, v17 offset1:1
	v_or_b32_e32 v14, s2, v30
	v_ashrrev_i32_e32 v15, 31, v14
	v_lshl_add_u64 v[14:15], v[14:15], 2, s[10:11]
	global_load_dword v14, v[14:15], off
	s_waitcnt vmcnt(0)
	v_pk_mul_f32 v[12:13], v[12:13], v[14:15] op_sel_hi:[1,0]
	v_pk_mul_f32 v[10:11], v[10:11], v[14:15] op_sel_hi:[1,0]
	v_add_u32_e32 v14, 0x14a0, v34
	ds_write2_b32 v14, v10, v11 offset1:1
	v_add_u32_e32 v10, 0x14a8, v34
	ds_write2_b32 v10, v12, v13 offset1:1
	v_or_b32_e32 v10, s2, v31
	v_ashrrev_i32_e32 v11, 31, v10
	v_lshl_add_u64 v[10:11], v[10:11], 2, s[10:11]
	global_load_dword v10, v[10:11], off
	s_waitcnt vmcnt(0)
	v_pk_mul_f32 v[8:9], v[8:9], v[10:11] op_sel_hi:[1,0]
	v_pk_mul_f32 v[6:7], v[6:7], v[10:11] op_sel_hi:[1,0]
	v_add_u32_e32 v10, 0x18c0, v34
	ds_write2_b32 v10, v6, v7 offset1:1
	v_add_u32_e32 v6, 0x18c8, v34
	ds_write2_b32 v6, v8, v9 offset1:1
	v_or_b32_e32 v6, s2, v32
	v_ashrrev_i32_e32 v7, 31, v6
	v_lshl_add_u64 v[6:7], v[6:7], 2, s[10:11]
	global_load_dword v6, v[6:7], off
	s_waitcnt vmcnt(0)
	v_pk_mul_f32 v[4:5], v[4:5], v[6:7] op_sel_hi:[1,0]
	v_pk_mul_f32 v[2:3], v[2:3], v[6:7] op_sel_hi:[1,0]
	v_add_u32_e32 v6, 0x1ce0, v34
	ds_write2_b32 v6, v2, v3 offset1:1
	v_add_u32_e32 v2, 0x1ce8, v34
	ds_write2_b32 v2, v4, v5 offset1:1
	s_waitcnt lgkmcnt(0)
	ds_read2_b32 v[8:9], v33 offset0:33 offset1:41
	ds_read2_b32 v[10:11], v33 offset1:8
	ds_read2_b32 v[12:13], v33 offset0:66 offset1:74
	ds_read2_b32 v[14:15], v33 offset0:99 offset1:107
	ds_read2_b32 v[16:17], v33 offset0:132 offset1:140
	ds_read2_b32 v[18:19], v33 offset0:165 offset1:173
	ds_read2_b32 v[20:21], v33 offset0:198 offset1:206
	ds_read2_b32 v[36:37], v33 offset0:231 offset1:239
	v_lshl_add_u64 v[6:7], s[2:3], 1, v[24:25]
	s_waitcnt lgkmcnt(6)
	v_cvt_pk_bf16_f32 v2, v10, v8
	s_waitcnt lgkmcnt(4)
	v_cvt_pk_bf16_f32 v3, v12, v14
	s_waitcnt lgkmcnt(2)
	v_cvt_pk_bf16_f32 v4, v16, v18
	s_waitcnt lgkmcnt(0)
	v_cvt_pk_bf16_f32 v5, v20, v36
	v_lshl_add_u64 v[40:41], v[6:7], 0, v[40:41]
	v_add_u32_e32 v8, 8, v38
	global_store_dwordx4 v[40:41], v[2:5], off
	v_add_u32_e32 v40, 16, v38
	v_ashrrev_i32_e32 v41, 31, v40
	v_cvt_pk_bf16_f32 v2, v11, v9
	v_ashrrev_i32_e32 v9, 31, v8
	v_lshlrev_b64 v[8:9], 11, v[8:9]
	v_cvt_pk_bf16_f32 v3, v13, v15
	v_cvt_pk_bf16_f32 v4, v17, v19
	v_cvt_pk_bf16_f32 v5, v21, v37
	v_lshl_add_u64 v[8:9], v[6:7], 0, v[8:9]
	global_store_dwordx4 v[8:9], v[2:5], off
	ds_read2_b32 v[8:9], v33 offset0:49 offset1:57
	ds_read2_b32 v[10:11], v33 offset0:16 offset1:24
	ds_read2_b32 v[12:13], v33 offset0:82 offset1:90
	ds_read2_b32 v[14:15], v33 offset0:115 offset1:123
	ds_read2_b32 v[16:17], v33 offset0:148 offset1:156
	ds_read2_b32 v[18:19], v33 offset0:181 offset1:189
	ds_read2_b32 v[20:21], v33 offset0:214 offset1:222
	ds_read2_b32 v[36:37], v33 offset0:247 offset1:255
	v_lshlrev_b64 v[40:41], 11, v[40:41]
	s_waitcnt lgkmcnt(6)
	v_cvt_pk_bf16_f32 v2, v10, v8
	s_waitcnt lgkmcnt(4)
	v_cvt_pk_bf16_f32 v3, v12, v14
	s_waitcnt lgkmcnt(2)
	v_cvt_pk_bf16_f32 v4, v16, v18
	s_waitcnt lgkmcnt(0)
	v_cvt_pk_bf16_f32 v5, v20, v36
	v_lshl_add_u64 v[40:41], v[6:7], 0, v[40:41]
	v_add_u32_e32 v8, 24, v38
	global_store_dwordx4 v[40:41], v[2:5], off
	s_nop 1
	v_cvt_pk_bf16_f32 v2, v11, v9
	v_ashrrev_i32_e32 v9, 31, v8
	v_lshlrev_b64 v[8:9], 11, v[8:9]
	v_cvt_pk_bf16_f32 v3, v13, v15
	v_cvt_pk_bf16_f32 v4, v17, v19
	v_cvt_pk_bf16_f32 v5, v21, v37
	v_lshl_add_u64 v[6:7], v[6:7], 0, v[8:9]
	global_store_dwordx4 v[6:7], v[2:5], off
	s_waitcnt lgkmcnt(0)
	s_cbranch_scc1 .LBB0_1263

; #define LAS __attribute__((address_space(3)))
; __device__ __forceinline__ unsigned pk2(float lo, float hi) { f32x2_t v = {lo, hi}; bf16x2_t b = __builtin_convertvector(v, bf16x2_t); return __builtin_bit_cast(unsigned, b); }
; __device__ __forceinline__ void transpose_item(const float* W, int K, int N, bf16* WT, const float* scale, LAS float* scr, int item, int lane) {
;     ...
;         const int q = lane & 7, r = lane >> 3;
;         f32x4 v[8];
; #pragma unroll
;         for (int i = 0; i < 8; ++i) v[i] = *(const f32x4*)(W + (size_t)(k0 + 8 * i + r) * N + n0 + 4 * q);
; #pragma unroll
;         for (int i = 0; i < 8; ++i) { const int kk = 8 * i + r; f32x4 x = v[i]; if (scale) x = x * scale[k0 + kk];
;             scr[kk * 33 + 4 * q + 0] = x[0]; scr[kk * 33 + 4 * q + 1] = x[1]; scr[kk * 33 + 4 * q + 2] = x[2]; scr[kk * 33 + 4 * q + 3] = x[3]; }
;     }
;     asm volatile("s_waitcnt lgkmcnt(0)" ::: "memory");
;     const int c = lane & 7;
; #pragma unroll
;     for (int j = 0; j < 4; ++j) { const int n = (lane >> 3) + 8 * j; const LAS float* s = scr + (8 * c) * 33 + n;
;         v4u o; o.x = pk2(s[0 * 33], s[1 * 33]); o.y = pk2(s[2 * 33], s[3 * 33]); o.z = pk2(s[4 * 33], s[5 * 33]); o.w = pk2(s[6 * 33], s[7 * 33]);
;         *(v4u*)(WT + (size_t)(n0 + n) * K + k0 + 8 * c) = o; }
;     asm volatile("s_waitcnt lgkmcnt(0)" ::: "memory");
.LBB0_1266:
	s_ashr_i32 s2, s8, 31
	s_lshr_b32 s2, s2, 27
	s_add_i32 s2, s8, s2
	s_ashr_i32 s2, s2, 5
	s_lshl_b32 s4, s2, 6
	s_lshl_b32 s2, s2, 10
	s_sub_i32 s2, s6, s2
	s_waitcnt vmcnt(24)
	v_or_b32_e32 v38, s4, v1
	s_ashr_i32 s3, s2, 31
	s_waitcnt vmcnt(22)
	v_ashrrev_i32_e32 v39, 31, v38
	v_or_b32_e32 v6, 8, v38
	v_lshl_add_u64 v[18:19], s[2:3], 2, v[14:15]
	v_lshlrev_b64 v[2:3], 12, v[38:39]
	v_ashrrev_i32_e32 v7, 31, v6
	v_lshl_add_u64 v[2:3], v[18:19], 0, v[2:3]
	v_lshlrev_b64 v[6:7], 12, v[6:7]
	v_or_b32_e32 v10, 16, v38
	global_load_dwordx4 v[2:5], v[2:3], off nt
	v_lshl_add_u64 v[6:7], v[18:19], 0, v[6:7]
	v_ashrrev_i32_e32 v11, 31, v10
	global_load_dwordx4 v[6:9], v[6:7], off nt
	v_lshlrev_b64 v[10:11], 12, v[10:11]
	v_or_b32_e32 v22, 24, v38
	v_lshl_add_u64 v[10:11], v[18:19], 0, v[10:11]
	v_ashrrev_i32_e32 v23, 31, v22
	global_load_dwordx4 v[10:13], v[10:11], off nt
	v_lshlrev_b64 v[22:23], 12, v[22:23]
	v_or_b32_e32 v26, 32, v38
	v_lshl_add_u64 v[22:23], v[18:19], 0, v[22:23]
	v_ashrrev_i32_e32 v27, 31, v26
	global_load_dwordx4 v[22:25], v[22:23], off nt
	v_lshlrev_b64 v[26:27], 12, v[26:27]
	v_or_b32_e32 v30, 40, v38
	v_lshl_add_u64 v[26:27], v[18:19], 0, v[26:27]
	v_ashrrev_i32_e32 v31, 31, v30
	global_load_dwordx4 v[26:29], v[26:27], off nt
	v_lshlrev_b64 v[30:31], 12, v[30:31]
	v_or_b32_e32 v34, 48, v38
	v_lshl_add_u64 v[30:31], v[18:19], 0, v[30:31]
	v_ashrrev_i32_e32 v35, 31, v34
	global_load_dwordx4 v[30:33], v[30:31], off nt
	v_lshlrev_b64 v[34:35], 12, v[34:35]
	v_or_b32_e32 v38, 56, v38
	v_lshl_add_u64 v[34:35], v[18:19], 0, v[34:35]
	v_ashrrev_i32_e32 v39, 31, v38
	global_load_dwordx4 v[34:37], v[34:35], off nt
	v_lshlrev_b64 v[38:39], 12, v[38:39]
	v_lshl_add_u64 v[18:19], v[18:19], 0, v[38:39]
	global_load_dwordx4 v[38:41], v[18:19], off nt
	s_ashr_i32 s5, s4, 31
	s_add_i32 s8, s8, s9
	s_add_i32 s6, s6, s7
	s_cmpk_lt_i32 s8, 0x200
	s_waitcnt vmcnt(7)
	ds_write2_b32 v21, v2, v3 offset1:1
	ds_write2_b32 v21, v4, v5 offset0:2 offset1:3
	v_add_u32_e32 v2, 0x420, v21
	s_waitcnt vmcnt(6)
	ds_write2_b32 v2, v6, v7 offset1:1
	v_add_u32_e32 v2, 0x428, v21
	ds_write2_b32 v2, v8, v9 offset1:1
	v_add_u32_e32 v2, 0x840, v21
	v_lshl_add_u64 v[6:7], s[4:5], 1, v[16:17]
	s_waitcnt vmcnt(5)
	ds_write2_b32 v2, v10, v11 offset1:1
	v_add_u32_e32 v2, 0x848, v21
	ds_write2_b32 v2, v12, v13 offset1:1
	v_add_u32_e32 v2, 0xc60, v21
	s_waitcnt vmcnt(4)
	ds_write2_b32 v2, v22, v23 offset1:1
	v_add_u32_e32 v2, 0xc68, v21
	ds_write2_b32 v2, v24, v25 offset1:1
	v_add_u32_e32 v2, 0x1080, v21
	s_waitcnt vmcnt(3)
	ds_write2_b32 v2, v26, v27 offset1:1
	v_add_u32_e32 v2, 0x1088, v21
	ds_write2_b32 v2, v28, v29 offset1:1
	v_add_u32_e32 v2, 0x14a0, v21
	s_waitcnt vmcnt(2)
	ds_write2_b32 v2, v30, v31 offset1:1
	v_add_u32_e32 v2, 0x14a8, v21
	ds_write2_b32 v2, v32, v33 offset1:1
	v_add_u32_e32 v2, 0x18c0, v21
	v_add_u32_e32 v30, s2, v1
	s_waitcnt vmcnt(1)
	ds_write2_b32 v2, v34, v35 offset1:1
	v_add_u32_e32 v2, 0x18c8, v21
	ds_write2_b32 v2, v36, v37 offset1:1
	v_add_u32_e32 v2, 0x1ce0, v21
	s_waitcnt vmcnt(0)
	ds_write2_b32 v2, v38, v39 offset1:1
	v_add_u32_e32 v2, 0x1ce8, v21
	ds_write2_b32 v2, v40, v41 offset1:1
	s_waitcnt lgkmcnt(0)
	ds_read2_b32 v[8:9], v20 offset0:33 offset1:41
	ds_read2_b32 v[10:11], v20 offset1:8
	ds_read2_b32 v[12:13], v20 offset0:66 offset1:74
	ds_read2_b32 v[18:19], v20 offset0:99 offset1:107
	ds_read2_b32 v[22:23], v20 offset0:132 offset1:140
	ds_read2_b32 v[24:25], v20 offset0:165 offset1:173
	ds_read2_b32 v[26:27], v20 offset0:198 offset1:206
	ds_read2_b32 v[28:29], v20 offset0:231 offset1:239
	v_ashrrev_i32_e32 v31, 31, v30
	v_lshlrev_b64 v[32:33], 11, v[30:31]
	s_waitcnt lgkmcnt(6)
	v_cvt_pk_bf16_f32 v2, v10, v8
	s_waitcnt lgkmcnt(4)
	v_cvt_pk_bf16_f32 v3, v12, v18
	s_waitcnt lgkmcnt(2)
	v_cvt_pk_bf16_f32 v4, v22, v24
	s_waitcnt lgkmcnt(0)
	v_cvt_pk_bf16_f32 v5, v26, v28
	v_lshl_add_u64 v[32:33], v[6:7], 0, v[32:33]
	v_add_u32_e32 v8, 8, v30
	global_store_dwordx4 v[32:33], v[2:5], off
	v_add_u32_e32 v32, 16, v30
	v_ashrrev_i32_e32 v33, 31, v32
	v_cvt_pk_bf16_f32 v2, v11, v9
	v_ashrrev_i32_e32 v9, 31, v8
	v_lshlrev_b64 v[8:9], 11, v[8:9]
	v_cvt_pk_bf16_f32 v3, v13, v19
	v_cvt_pk_bf16_f32 v4, v23, v25
	v_cvt_pk_bf16_f32 v5, v27, v29
	v_lshl_add_u64 v[8:9], v[6:7], 0, v[8:9]
	global_store_dwordx4 v[8:9], v[2:5], off
	ds_read2_b32 v[8:9], v20 offset0:49 offset1:57
	ds_read2_b32 v[10:11], v20 offset0:16 offset1:24
	ds_read2_b32 v[12:13], v20 offset0:82 offset1:90
	ds_read2_b32 v[18:19], v20 offset0:115 offset1:123
	ds_read2_b32 v[22:23], v20 offset0:148 offset1:156
	ds_read2_b32 v[24:25], v20 offset0:181 offset1:189
	ds_read2_b32 v[26:27], v20 offset0:214 offset1:222
	ds_read2_b32 v[28:29], v20 offset0:247 offset1:255
	v_lshlrev_b64 v[32:33], 11, v[32:33]
	s_waitcnt lgkmcnt(6)
	v_cvt_pk_bf16_f32 v2, v10, v8
	s_waitcnt lgkmcnt(4)
	v_cvt_pk_bf16_f32 v3, v12, v18
	s_waitcnt lgkmcnt(2)
	v_cvt_pk_bf16_f32 v4, v22, v24
	s_waitcnt lgkmcnt(0)
	v_cvt_pk_bf16_f32 v5, v26, v28
	v_lshl_add_u64 v[32:33], v[6:7], 0, v[32:33]
	v_add_u32_e32 v8, 24, v30
	global_store_dwordx4 v[32:33], v[2:5], off
	s_nop 1
	v_cvt_pk_bf16_f32 v2, v11, v9
	v_ashrrev_i32_e32 v9, 31, v8
	v_lshlrev_b64 v[8:9], 11, v[8:9]
	v_cvt_pk_bf16_f32 v3, v13, v19
	v_cvt_pk_bf16_f32 v4, v23, v25
	v_cvt_pk_bf16_f32 v5, v27, v29
	v_lshl_add_u64 v[6:7], v[6:7], 0, v[8:9]
	global_store_dwordx4 v[6:7], v[2:5], off
	s_waitcnt lgkmcnt(0)
	s_cbranch_scc1 .LBB0_1266
	v_readlane_b32 s50, v255, 24
	v_readlane_b32 s51, v255, 25

; #define LAS __attribute__((address_space(3)))
; __device__ __forceinline__ unsigned pk2(float lo, float hi) { f32x2_t v = {lo, hi}; bf16x2_t b = __builtin_convertvector(v, bf16x2_t); return __builtin_bit_cast(unsigned, b); }
; __device__ __forceinline__ void transpose_item(const float* W, int K, int N, bf16* WT, const float* scale, LAS float* scr, int item, int lane) {
;     ...
;         const int q = lane & 7, r = lane >> 3;
;         f32x4 v[8];
; #pragma unroll
;         for (int i = 0; i < 8; ++i) v[i] = *(const f32x4*)(W + (size_t)(k0 + 8 * i + r) * N + n0 + 4 * q);
; #pragma unroll
;         for (int i = 0; i < 8; ++i) { const int kk = 8 * i + r; f32x4 x = v[i]; if (scale) x = x * scale[k0 + kk];
;             scr[kk * 33 + 4 * q + 0] = x[0]; scr[kk * 33 + 4 * q + 1] = x[1]; scr[kk * 33 + 4 * q + 2] = x[2]; scr[kk * 33 + 4 * q + 3] = x[3]; }
;     }
;     asm volatile("s_waitcnt lgkmcnt(0)" ::: "memory");
;     const int c = lane & 7;
; #pragma unroll
;     for (int j = 0; j < 4; ++j) { const int n = (lane >> 3) + 8 * j; const LAS float* s = scr + (8 * c) * 33 + n;
;         v4u o; o.x = pk2(s[0 * 33], s[1 * 33]); o.y = pk2(s[2 * 33], s[3 * 33]); o.z = pk2(s[4 * 33], s[5 * 33]); o.w = pk2(s[6 * 33], s[7 * 33]);
;         *(v4u*)(WT + (size_t)(n0 + n) * K + k0 + 8 * c) = o; }
;     asm volatile("s_waitcnt lgkmcnt(0)" ::: "memory");
.LBB0_1270:
	s_mul_hi_i32 s2, s8, 0x2aaaaaab
	s_lshr_b32 s3, s2, 31
	s_ashr_i32 s2, s2, 4
	s_add_i32 s2, s2, s3
	s_lshl_b32 s4, s2, 6
	s_mulk_i32 s2, 0xf400
	s_add_i32 s2, s6, s2
	s_ashr_i32 s3, s2, 31
	s_waitcnt vmcnt(1)
	v_or_b32_e32 v48, s4, v1
	v_lshl_add_u64 v[2:3], s[2:3], 2, v[22:23]
	v_mad_i64_i32 v[4:5], s[10:11], v48, s14, v[2:3]
	global_load_dwordx4 v[36:39], v[4:5], off nt
	v_or_b32_e32 v4, 8, v48
	v_mad_i64_i32 v[4:5], s[10:11], v4, s14, v[2:3]
	global_load_dwordx4 v[40:43], v[4:5], off nt
	v_or_b32_e32 v4, 16, v48
	v_mad_i64_i32 v[4:5], s[10:11], v4, s14, v[2:3]
	global_load_dwordx4 v[44:47], v[4:5], off nt
	v_or_b32_e32 v4, 24, v48
	v_mad_i64_i32 v[4:5], s[10:11], v4, s14, v[2:3]
	global_load_dwordx4 v[18:21], v[4:5], off nt
	v_or_b32_e32 v4, 32, v48
	v_mad_i64_i32 v[4:5], s[10:11], v4, s14, v[2:3]
	global_load_dwordx4 v[14:17], v[4:5], off nt
	v_or_b32_e32 v4, 40, v48
	v_mad_i64_i32 v[4:5], s[10:11], v4, s14, v[2:3]
	global_load_dwordx4 v[10:13], v[4:5], off nt
	v_or_b32_e32 v4, 48, v48
	v_ashrrev_i32_e32 v49, 31, v48
	v_mad_i64_i32 v[4:5], s[10:11], v4, s14, v[2:3]
	global_load_dwordx4 v[6:9], v[4:5], off nt
	v_or_b32_e32 v4, 56, v48
	v_lshl_add_u64 v[48:49], v[48:49], 2, s[12:13]
	global_load_dword v48, v[48:49], off
	v_mad_i64_i32 v[2:3], s[10:11], v4, s14, v[2:3]
	global_load_dwordx4 v[2:5], v[2:3], off nt
	v_add_u32_e32 v35, 0x420, v34
	s_ashr_i32 s5, s4, 31
	s_add_i32 s8, s8, s9
	s_add_i32 s6, s6, s7
	s_cmpk_lt_i32 s8, 0x600
	s_waitcnt vmcnt(1)
	v_pk_mul_f32 v[36:37], v[36:37], v[48:49] op_sel_hi:[1,0]
	v_pk_mul_f32 v[38:39], v[38:39], v[48:49] op_sel_hi:[1,0]
	ds_write2_b32 v34, v36, v37 offset1:1
	ds_write2_b32 v34, v38, v39 offset0:2 offset1:3
	v_or_b32_e32 v36, s4, v26
	v_ashrrev_i32_e32 v37, 31, v36
	v_lshl_add_u64 v[36:37], v[36:37], 2, s[12:13]
	global_load_dword v36, v[36:37], off
	s_waitcnt vmcnt(0)
	v_pk_mul_f32 v[38:39], v[42:43], v[36:37] op_sel_hi:[1,0]
	v_pk_mul_f32 v[36:37], v[40:41], v[36:37] op_sel_hi:[1,0]
	ds_write2_b32 v35, v36, v37 offset1:1
	v_or_b32_e32 v36, s4, v27
	v_ashrrev_i32_e32 v37, 31, v36
	v_lshl_add_u64 v[36:37], v[36:37], 2, s[12:13]
	global_load_dword v36, v[36:37], off
	v_add_u32_e32 v35, 0x428, v34
	ds_write2_b32 v35, v38, v39 offset1:1
	v_add_u32_e32 v35, 0x840, v34
	s_waitcnt vmcnt(0)
	v_pk_mul_f32 v[38:39], v[46:47], v[36:37] op_sel_hi:[1,0]
	v_pk_mul_f32 v[36:37], v[44:45], v[36:37] op_sel_hi:[1,0]
	ds_write2_b32 v35, v36, v37 offset1:1
	v_or_b32_e32 v36, s4, v28
	v_ashrrev_i32_e32 v37, 31, v36
	v_lshl_add_u64 v[36:37], v[36:37], 2, s[12:13]
	global_load_dword v36, v[36:37], off
	v_add_u32_e32 v35, 0x848, v34
	ds_write2_b32 v35, v38, v39 offset1:1
	v_add_u32_e32 v35, 0xc60, v34
	v_add_u32_e32 v38, s2, v1
	v_ashrrev_i32_e32 v39, 31, v38
	v_lshlrev_b64 v[40:41], 11, v[38:39]
	s_waitcnt vmcnt(0)
	v_pk_mul_f32 v[18:19], v[18:19], v[36:37] op_sel_hi:[1,0]
	v_pk_mul_f32 v[20:21], v[20:21], v[36:37] op_sel_hi:[1,0]
	ds_write2_b32 v35, v18, v19 offset1:1
	v_add_u32_e32 v18, 0xc68, v34
	ds_write2_b32 v18, v20, v21 offset1:1
	v_or_b32_e32 v18, s4, v29
	v_ashrrev_i32_e32 v19, 31, v18
	v_lshl_add_u64 v[18:19], v[18:19], 2, s[12:13]
	global_load_dword v18, v[18:19], off
	s_waitcnt vmcnt(0)
	v_pk_mul_f32 v[16:17], v[16:17], v[18:19] op_sel_hi:[1,0]
	v_pk_mul_f32 v[14:15], v[14:15], v[18:19] op_sel_hi:[1,0]
	v_add_u32_e32 v18, 0x1080, v34
	ds_write2_b32 v18, v14, v15 offset1:1
	v_add_u32_e32 v14, 0x1088, v34
	ds_write2_b32 v14, v16, v17 offset1:1
	v_or_b32_e32 v14, s4, v30
	v_ashrrev_i32_e32 v15, 31, v14
	v_lshl_add_u64 v[14:15], v[14:15], 2, s[12:13]
	global_load_dword v14, v[14:15], off
	s_waitcnt vmcnt(0)
	v_pk_mul_f32 v[12:13], v[12:13], v[14:15] op_sel_hi:[1,0]
	v_pk_mul_f32 v[10:11], v[10:11], v[14:15] op_sel_hi:[1,0]
	v_add_u32_e32 v14, 0x14a0, v34
	ds_write2_b32 v14, v10, v11 offset1:1
	v_add_u32_e32 v10, 0x14a8, v34
	ds_write2_b32 v10, v12, v13 offset1:1
	v_or_b32_e32 v10, s4, v31
	v_ashrrev_i32_e32 v11, 31, v10
	v_lshl_add_u64 v[10:11], v[10:11], 2, s[12:13]
	global_load_dword v10, v[10:11], off
	s_waitcnt vmcnt(0)
	v_pk_mul_f32 v[8:9], v[8:9], v[10:11] op_sel_hi:[1,0]
	v_pk_mul_f32 v[6:7], v[6:7], v[10:11] op_sel_hi:[1,0]
	v_add_u32_e32 v10, 0x18c0, v34
	ds_write2_b32 v10, v6, v7 offset1:1
	v_add_u32_e32 v6, 0x18c8, v34
	ds_write2_b32 v6, v8, v9 offset1:1
	v_or_b32_e32 v6, s4, v32
	v_ashrrev_i32_e32 v7, 31, v6
	v_lshl_add_u64 v[6:7], v[6:7], 2, s[12:13]
	global_load_dword v6, v[6:7], off
	s_waitcnt vmcnt(0)
	v_pk_mul_f32 v[4:5], v[4:5], v[6:7] op_sel_hi:[1,0]
	v_pk_mul_f32 v[2:3], v[2:3], v[6:7] op_sel_hi:[1,0]
	v_add_u32_e32 v6, 0x1ce0, v34
	ds_write2_b32 v6, v2, v3 offset1:1
	v_add_u32_e32 v2, 0x1ce8, v34
	ds_write2_b32 v2, v4, v5 offset1:1
	s_waitcnt lgkmcnt(0)
	ds_read2_b32 v[8:9], v33 offset0:33 offset1:41
	ds_read2_b32 v[10:11], v33 offset1:8
	ds_read2_b32 v[12:13], v33 offset0:66 offset1:74
	ds_read2_b32 v[14:15], v33 offset0:99 offset1:107
	ds_read2_b32 v[16:17], v33 offset0:132 offset1:140
	ds_read2_b32 v[18:19], v33 offset0:165 offset1:173
	ds_read2_b32 v[20:21], v33 offset0:198 offset1:206
	ds_read2_b32 v[36:37], v33 offset0:231 offset1:239
	v_lshl_add_u64 v[6:7], s[4:5], 1, v[24:25]
	s_waitcnt lgkmcnt(6)
	v_cvt_pk_bf16_f32 v2, v10, v8
	s_waitcnt lgkmcnt(4)
	v_cvt_pk_bf16_f32 v3, v12, v14
	s_waitcnt lgkmcnt(2)
	v_cvt_pk_bf16_f32 v4, v16, v18
	s_waitcnt lgkmcnt(0)
	v_cvt_pk_bf16_f32 v5, v20, v36
	v_lshl_add_u64 v[40:41], v[6:7], 0, v[40:41]
	v_add_u32_e32 v8, 8, v38
	global_store_dwordx4 v[40:41], v[2:5], off
	v_add_u32_e32 v40, 16, v38
	v_ashrrev_i32_e32 v41, 31, v40
	v_cvt_pk_bf16_f32 v2, v11, v9
	v_ashrrev_i32_e32 v9, 31, v8
	v_lshlrev_b64 v[8:9], 11, v[8:9]
	v_cvt_pk_bf16_f32 v3, v13, v15
	v_cvt_pk_bf16_f32 v4, v17, v19
	v_cvt_pk_bf16_f32 v5, v21, v37
	v_lshl_add_u64 v[8:9], v[6:7], 0, v[8:9]
	global_store_dwordx4 v[8:9], v[2:5], off
	ds_read2_b32 v[8:9], v33 offset0:49 offset1:57
	ds_read2_b32 v[10:11], v33 offset0:16 offset1:24
	ds_read2_b32 v[12:13], v33 offset0:82 offset1:90
	ds_read2_b32 v[14:15], v33 offset0:115 offset1:123
	ds_read2_b32 v[16:17], v33 offset0:148 offset1:156
	ds_read2_b32 v[18:19], v33 offset0:181 offset1:189
	ds_read2_b32 v[20:21], v33 offset0:214 offset1:222
	ds_read2_b32 v[36:37], v33 offset0:247 offset1:255
	v_lshlrev_b64 v[40:41], 11, v[40:41]
	s_waitcnt lgkmcnt(6)
	v_cvt_pk_bf16_f32 v2, v10, v8
	s_waitcnt lgkmcnt(4)
	v_cvt_pk_bf16_f32 v3, v12, v14
	s_waitcnt lgkmcnt(2)
	v_cvt_pk_bf16_f32 v4, v16, v18
	s_waitcnt lgkmcnt(0)
	v_cvt_pk_bf16_f32 v5, v20, v36
	v_lshl_add_u64 v[40:41], v[6:7], 0, v[40:41]
	v_add_u32_e32 v8, 24, v38
	global_store_dwordx4 v[40:41], v[2:5], off
	s_nop 1
	v_cvt_pk_bf16_f32 v2, v11, v9
	v_ashrrev_i32_e32 v9, 31, v8
	v_lshlrev_b64 v[8:9], 11, v[8:9]
	v_cvt_pk_bf16_f32 v3, v13, v15
	v_cvt_pk_bf16_f32 v4, v17, v19
	v_cvt_pk_bf16_f32 v5, v21, v37
	v_lshl_add_u64 v[6:7], v[6:7], 0, v[8:9]
	global_store_dwordx4 v[6:7], v[2:5], off
	s_waitcnt lgkmcnt(0)
	s_cbranch_scc1 .LBB0_1270
	v_readlane_b32 s50, v255, 24
	v_readlane_b32 s51, v255, 25

; #define LAS __attribute__((address_space(3)))
; __device__ __forceinline__ unsigned pk2(float lo, float hi) { f32x2_t v = {lo, hi}; bf16x2_t b = __builtin_convertvector(v, bf16x2_t); return __builtin_bit_cast(unsigned, b); }
; __device__ __forceinline__ void transpose_item(const float* W, int K, int N, bf16* WT, const float* scale, LAS float* scr, int item, int lane) {
;     ...
;         const int q = lane & 7, r = lane >> 3;
;         f32x4 v[8];
; #pragma unroll
;         for (int i = 0; i < 8; ++i) v[i] = *(const f32x4*)(W + (size_t)(k0 + 8 * i + r) * N + n0 + 4 * q);
; #pragma unroll
;         for (int i = 0; i < 8; ++i) { const int kk = 8 * i + r; f32x4 x = v[i]; if (scale) x = x * scale[k0 + kk];
;             scr[kk * 33 + 4 * q + 0] = x[0]; scr[kk * 33 + 4 * q + 1] = x[1]; scr[kk * 33 + 4 * q + 2] = x[2]; scr[kk * 33 + 4 * q + 3] = x[3]; }
;     }
;     asm volatile("s_waitcnt lgkmcnt(0)" ::: "memory");
;     const int c = lane & 7;
; #pragma unroll
;     for (int j = 0; j < 4; ++j) { const int n = (lane >> 3) + 8 * j; const LAS float* s = scr + (8 * c) * 33 + n;
;         v4u o; o.x = pk2(s[0 * 33], s[1 * 33]); o.y = pk2(s[2 * 33], s[3 * 33]); o.z = pk2(s[4 * 33], s[5 * 33]); o.w = pk2(s[6 * 33], s[7 * 33]);
;         *(v4u*)(WT + (size_t)(n0 + n) * K + k0 + 8 * c) = o; }
;     asm volatile("s_waitcnt lgkmcnt(0)" ::: "memory");
.LBB0_1274:
	s_ashr_i32 s0, s6, 31
	s_lshr_b32 s0, s0, 27
	s_add_i32 s0, s6, s0
	s_ashr_i32 s0, s0, 5
	s_lshl_b32 s2, s0, 6
	s_lshl_b32 s0, s0, 10
	s_sub_i32 s0, s4, s0
	s_waitcnt vmcnt(24)
	v_or_b32_e32 v38, s2, v1
	s_ashr_i32 s1, s0, 31
	s_waitcnt vmcnt(22)
	v_ashrrev_i32_e32 v39, 31, v38
	v_or_b32_e32 v6, 8, v38
	v_lshl_add_u64 v[18:19], s[0:1], 2, v[14:15]
	v_lshlrev_b64 v[2:3], 12, v[38:39]
	v_ashrrev_i32_e32 v7, 31, v6
	v_lshl_add_u64 v[2:3], v[18:19], 0, v[2:3]
	v_lshlrev_b64 v[6:7], 12, v[6:7]
	v_or_b32_e32 v10, 16, v38
	global_load_dwordx4 v[2:5], v[2:3], off nt
	v_lshl_add_u64 v[6:7], v[18:19], 0, v[6:7]
	v_ashrrev_i32_e32 v11, 31, v10
	global_load_dwordx4 v[6:9], v[6:7], off nt
	v_lshlrev_b64 v[10:11], 12, v[10:11]
	v_or_b32_e32 v22, 24, v38
	v_lshl_add_u64 v[10:11], v[18:19], 0, v[10:11]
	v_ashrrev_i32_e32 v23, 31, v22
	global_load_dwordx4 v[10:13], v[10:11], off nt
	v_lshlrev_b64 v[22:23], 12, v[22:23]
	v_or_b32_e32 v26, 32, v38
	v_lshl_add_u64 v[22:23], v[18:19], 0, v[22:23]
	v_ashrrev_i32_e32 v27, 31, v26
	global_load_dwordx4 v[22:25], v[22:23], off nt
	v_lshlrev_b64 v[26:27], 12, v[26:27]
	v_or_b32_e32 v30, 40, v38
	v_lshl_add_u64 v[26:27], v[18:19], 0, v[26:27]
	v_ashrrev_i32_e32 v31, 31, v30
	global_load_dwordx4 v[26:29], v[26:27], off nt
	v_lshlrev_b64 v[30:31], 12, v[30:31]
	v_or_b32_e32 v34, 48, v38
	v_lshl_add_u64 v[30:31], v[18:19], 0, v[30:31]
	v_ashrrev_i32_e32 v35, 31, v34
	global_load_dwordx4 v[30:33], v[30:31], off nt
	v_lshlrev_b64 v[34:35], 12, v[34:35]
	v_or_b32_e32 v38, 56, v38
	v_lshl_add_u64 v[34:35], v[18:19], 0, v[34:35]
	v_ashrrev_i32_e32 v39, 31, v38
	global_load_dwordx4 v[34:37], v[34:35], off nt
	v_lshlrev_b64 v[38:39], 12, v[38:39]
	v_lshl_add_u64 v[18:19], v[18:19], 0, v[38:39]
	global_load_dwordx4 v[38:41], v[18:19], off nt
	s_ashr_i32 s3, s2, 31
	s_add_i32 s6, s6, s7
	s_add_i32 s4, s4, s5
	s_cmpk_lt_i32 s6, 0x200
	s_waitcnt vmcnt(7)
	ds_write2_b32 v21, v2, v3 offset1:1
	ds_write2_b32 v21, v4, v5 offset0:2 offset1:3
	v_add_u32_e32 v2, 0x420, v21
	s_waitcnt vmcnt(6)
	ds_write2_b32 v2, v6, v7 offset1:1
	v_add_u32_e32 v2, 0x428, v21
	ds_write2_b32 v2, v8, v9 offset1:1
	v_add_u32_e32 v2, 0x840, v21
	v_lshl_add_u64 v[6:7], s[2:3], 1, v[16:17]
	s_waitcnt vmcnt(5)
	ds_write2_b32 v2, v10, v11 offset1:1
	v_add_u32_e32 v2, 0x848, v21
	ds_write2_b32 v2, v12, v13 offset1:1
	v_add_u32_e32 v2, 0xc60, v21
	s_waitcnt vmcnt(4)
	ds_write2_b32 v2, v22, v23 offset1:1
	v_add_u32_e32 v2, 0xc68, v21
	ds_write2_b32 v2, v24, v25 offset1:1
	v_add_u32_e32 v2, 0x1080, v21
	s_waitcnt vmcnt(3)
	ds_write2_b32 v2, v26, v27 offset1:1
	v_add_u32_e32 v2, 0x1088, v21
	ds_write2_b32 v2, v28, v29 offset1:1
	v_add_u32_e32 v2, 0x14a0, v21
	s_waitcnt vmcnt(2)
	ds_write2_b32 v2, v30, v31 offset1:1
	v_add_u32_e32 v2, 0x14a8, v21
	ds_write2_b32 v2, v32, v33 offset1:1
	v_add_u32_e32 v2, 0x18c0, v21
	v_add_u32_e32 v30, s0, v1
	s_waitcnt vmcnt(1)
	ds_write2_b32 v2, v34, v35 offset1:1
	v_add_u32_e32 v2, 0x18c8, v21
	ds_write2_b32 v2, v36, v37 offset1:1
	v_add_u32_e32 v2, 0x1ce0, v21
	s_waitcnt vmcnt(0)
	ds_write2_b32 v2, v38, v39 offset1:1
	v_add_u32_e32 v2, 0x1ce8, v21
	ds_write2_b32 v2, v40, v41 offset1:1
	s_waitcnt lgkmcnt(0)
	ds_read2_b32 v[8:9], v20 offset0:33 offset1:41
	ds_read2_b32 v[10:11], v20 offset1:8
	ds_read2_b32 v[12:13], v20 offset0:66 offset1:74
	ds_read2_b32 v[18:19], v20 offset0:99 offset1:107
	ds_read2_b32 v[22:23], v20 offset0:132 offset1:140
	ds_read2_b32 v[24:25], v20 offset0:165 offset1:173
	ds_read2_b32 v[26:27], v20 offset0:198 offset1:206
	ds_read2_b32 v[28:29], v20 offset0:231 offset1:239
	v_ashrrev_i32_e32 v31, 31, v30
	v_lshlrev_b64 v[32:33], 11, v[30:31]
	s_waitcnt lgkmcnt(6)
	v_cvt_pk_bf16_f32 v2, v10, v8
	s_waitcnt lgkmcnt(4)
	v_cvt_pk_bf16_f32 v3, v12, v18
	s_waitcnt lgkmcnt(2)
	v_cvt_pk_bf16_f32 v4, v22, v24
	s_waitcnt lgkmcnt(0)
	v_cvt_pk_bf16_f32 v5, v26, v28
	v_lshl_add_u64 v[32:33], v[6:7], 0, v[32:33]
	v_add_u32_e32 v8, 8, v30
	global_store_dwordx4 v[32:33], v[2:5], off
	v_add_u32_e32 v32, 16, v30
	v_ashrrev_i32_e32 v33, 31, v32
	v_cvt_pk_bf16_f32 v2, v11, v9
	v_ashrrev_i32_e32 v9, 31, v8
	v_lshlrev_b64 v[8:9], 11, v[8:9]
	v_cvt_pk_bf16_f32 v3, v13, v19
	v_cvt_pk_bf16_f32 v4, v23, v25
	v_cvt_pk_bf16_f32 v5, v27, v29
	v_lshl_add_u64 v[8:9], v[6:7], 0, v[8:9]
	global_store_dwordx4 v[8:9], v[2:5], off
	ds_read2_b32 v[8:9], v20 offset0:49 offset1:57
	ds_read2_b32 v[10:11], v20 offset0:16 offset1:24
	ds_read2_b32 v[12:13], v20 offset0:82 offset1:90
	ds_read2_b32 v[18:19], v20 offset0:115 offset1:123
	ds_read2_b32 v[22:23], v20 offset0:148 offset1:156
	ds_read2_b32 v[24:25], v20 offset0:181 offset1:189
	ds_read2_b32 v[26:27], v20 offset0:214 offset1:222
	ds_read2_b32 v[28:29], v20 offset0:247 offset1:255
	v_lshlrev_b64 v[32:33], 11, v[32:33]
	s_waitcnt lgkmcnt(6)
	v_cvt_pk_bf16_f32 v2, v10, v8
	s_waitcnt lgkmcnt(4)
	v_cvt_pk_bf16_f32 v3, v12, v18
	s_waitcnt lgkmcnt(2)
	v_cvt_pk_bf16_f32 v4, v22, v24
	s_waitcnt lgkmcnt(0)
	v_cvt_pk_bf16_f32 v5, v26, v28
	v_lshl_add_u64 v[32:33], v[6:7], 0, v[32:33]
	v_add_u32_e32 v8, 24, v30
	global_store_dwordx4 v[32:33], v[2:5], off
	s_nop 1
	v_cvt_pk_bf16_f32 v2, v11, v9
	v_ashrrev_i32_e32 v9, 31, v8
	v_lshlrev_b64 v[8:9], 11, v[8:9]
	v_cvt_pk_bf16_f32 v3, v13, v19
	v_cvt_pk_bf16_f32 v4, v23, v25
	v_cvt_pk_bf16_f32 v5, v27, v29
	v_lshl_add_u64 v[6:7], v[6:7], 0, v[8:9]
	global_store_dwordx4 v[6:7], v[2:5], off
	s_waitcnt lgkmcnt(0)
	s_cbranch_scc1 .LBB0_1274
	v_readlane_b32 s50, v255, 24
	v_readlane_b32 s51, v255, 25

; __device__ __forceinline__ void transpose_item(const float* W, int K, int N, bf16* WT, const float* scale, LAS float* scr, int item, int lane) {
;     ...
;         const int q = lane & 7, r = lane >> 3;
;         f32x4 v[8];
; #pragma unroll
;         for (int i = 0; i < 8; ++i) v[i] = *(const f32x4*)(W + (size_t)(k0 + 8 * i + r) * N + n0 + 4 * q);
; #pragma unroll
;         for (int i = 0; i < 8; ++i) { const int kk = 8 * i + r; f32x4 x = v[i]; if (scale) x = x * scale[k0 + kk];
;             scr[kk * 33 + 4 * q + 0] = x[0]; scr[kk * 33 + 4 * q + 1] = x[1]; scr[kk * 33 + 4 * q + 2] = x[2]; scr[kk * 33 + 4 * q + 3] = x[3]; }
;     }
;     asm volatile("s_waitcnt lgkmcnt(0)" ::: "memory");
.LBB0_1278:
	s_ashr_i32 s0, s6, 31
	s_lshr_b32 s0, s0, 25
	s_add_i32 s0, s6, s0
	s_ashr_i32 s0, s0, 7
	s_lshl_b32 s2, s0, 6
	s_lshl_b32 s0, s0, 12
	s_sub_i32 s0, s4, s0
	s_waitcnt vmcnt(1)
	v_or_b32_e32 v48, s2, v1
	s_ashr_i32 s1, s0, 31
	v_ashrrev_i32_e32 v49, 31, v48
	v_lshl_add_u64 v[2:3], s[0:1], 2, v[26:27]
	v_lshlrev_b64 v[4:5], 14, v[48:49]
	v_lshl_add_u64 v[4:5], v[2:3], 0, v[4:5]
	global_load_dwordx4 v[30:33], v[4:5], off nt
	v_or_b32_e32 v4, 8, v48
	v_ashrrev_i32_e32 v5, 31, v4
	v_lshlrev_b64 v[4:5], 14, v[4:5]
	v_lshl_add_u64 v[4:5], v[2:3], 0, v[4:5]
	global_load_dwordx4 v[44:47], v[4:5], off nt
	v_or_b32_e32 v4, 16, v48
	v_ashrrev_i32_e32 v5, 31, v4
	v_lshlrev_b64 v[4:5], 14, v[4:5]
	v_lshl_add_u64 v[4:5], v[2:3], 0, v[4:5]
	global_load_dwordx4 v[22:25], v[4:5], off nt
	v_or_b32_e32 v4, 24, v48
	v_ashrrev_i32_e32 v5, 31, v4
	v_lshlrev_b64 v[4:5], 14, v[4:5]
	v_lshl_add_u64 v[4:5], v[2:3], 0, v[4:5]
	global_load_dwordx4 v[18:21], v[4:5], off nt
	v_or_b32_e32 v4, 32, v48
	v_ashrrev_i32_e32 v5, 31, v4
	v_lshlrev_b64 v[4:5], 14, v[4:5]
	v_lshl_add_u64 v[4:5], v[2:3], 0, v[4:5]
	global_load_dwordx4 v[14:17], v[4:5], off nt
	v_or_b32_e32 v4, 40, v48
	v_ashrrev_i32_e32 v5, 31, v4
	v_lshlrev_b64 v[4:5], 14, v[4:5]
	v_lshl_add_u64 v[4:5], v[2:3], 0, v[4:5]
	global_load_dwordx4 v[10:13], v[4:5], off nt
	v_or_b32_e32 v4, 48, v48
	v_ashrrev_i32_e32 v5, 31, v4
	v_lshlrev_b64 v[4:5], 14, v[4:5]
	v_lshl_add_u64 v[4:5], v[2:3], 0, v[4:5]
	global_load_dwordx4 v[6:9], v[4:5], off nt
	v_or_b32_e32 v4, 56, v48
	v_lshl_add_u64 v[48:49], v[48:49], 2, s[8:9]
	global_load_dword v48, v[48:49], off
	v_ashrrev_i32_e32 v5, 31, v4
	v_lshlrev_b64 v[4:5], 14, v[4:5]
	v_lshl_add_u64 v[2:3], v[2:3], 0, v[4:5]
	global_load_dwordx4 v[2:5], v[2:3], off nt
	v_add_u32_e32 v43, 0x420, v42
	s_ashr_i32 s3, s2, 31
	s_add_i32 s6, s6, s7
	s_add_i32 s4, s4, s5
	s_cmpk_lt_i32 s6, 0x800
	s_waitcnt vmcnt(1)
	v_pk_mul_f32 v[30:31], v[30:31], v[48:49] op_sel_hi:[1,0]
	v_pk_mul_f32 v[32:33], v[32:33], v[48:49] op_sel_hi:[1,0]
	ds_write2_b32 v42, v30, v31 offset1:1
	ds_write2_b32 v42, v32, v33 offset0:2 offset1:3
	v_or_b32_e32 v30, s2, v34
	v_ashrrev_i32_e32 v31, 31, v30
	v_lshl_add_u64 v[30:31], v[30:31], 2, s[8:9]
	global_load_dword v32, v[30:31], off
	s_waitcnt vmcnt(0)
	v_pk_mul_f32 v[30:31], v[46:47], v[32:33] op_sel_hi:[1,0]
	v_pk_mul_f32 v[32:33], v[44:45], v[32:33] op_sel_hi:[1,0]
	ds_write2_b32 v43, v32, v33 offset1:1
	v_add_u32_e32 v32, 0x428, v42
	ds_write2_b32 v32, v30, v31 offset1:1
	v_or_b32_e32 v30, s2, v35
	v_ashrrev_i32_e32 v31, 31, v30
	v_lshl_add_u64 v[30:31], v[30:31], 2, s[8:9]
	global_load_dword v30, v[30:31], off
	s_waitcnt vmcnt(0)
	v_pk_mul_f32 v[24:25], v[24:25], v[30:31] op_sel_hi:[1,0]
	v_pk_mul_f32 v[22:23], v[22:23], v[30:31] op_sel_hi:[1,0]
	v_add_u32_e32 v30, 0x840, v42
	ds_write2_b32 v30, v22, v23 offset1:1
	v_add_u32_e32 v22, 0x848, v42
	ds_write2_b32 v22, v24, v25 offset1:1
	v_or_b32_e32 v22, s2, v36
	v_ashrrev_i32_e32 v23, 31, v22
	v_lshl_add_u64 v[22:23], v[22:23], 2, s[8:9]
	global_load_dword v22, v[22:23], off
	v_add_u32_e32 v24, s0, v1
	v_ashrrev_i32_e32 v25, 31, v24
	v_lshlrev_b64 v[30:31], 11, v[24:25]
	s_waitcnt vmcnt(0)
	v_pk_mul_f32 v[20:21], v[20:21], v[22:23] op_sel_hi:[1,0]
	v_pk_mul_f32 v[18:19], v[18:19], v[22:23] op_sel_hi:[1,0]
	v_add_u32_e32 v22, 0xc60, v42
	ds_write2_b32 v22, v18, v19 offset1:1
	v_add_u32_e32 v18, 0xc68, v42
	ds_write2_b32 v18, v20, v21 offset1:1
	v_or_b32_e32 v18, s2, v37
	v_ashrrev_i32_e32 v19, 31, v18
	v_lshl_add_u64 v[18:19], v[18:19], 2, s[8:9]
	global_load_dword v18, v[18:19], off
	s_waitcnt vmcnt(0)
; #define LAS __attribute__((address_space(3)))
; __device__ __forceinline__ unsigned pk2(float lo, float hi) { f32x2_t v = {lo, hi}; bf16x2_t b = __builtin_convertvector(v, bf16x2_t); return __builtin_bit_cast(unsigned, b); }
; __device__ __forceinline__ void transpose_item(const float* W, int K, int N, bf16* WT, const float* scale, LAS float* scr, int item, int lane) {
;     ...
;         for (int i = 0; i < 8; ++i) { const int kk = 8 * i + r; f32x4 x = v[i]; if (scale) x = x * scale[k0 + kk];
;             scr[kk * 33 + 4 * q + 0] = x[0]; scr[kk * 33 + 4 * q + 1] = x[1]; scr[kk * 33 + 4 * q + 2] = x[2]; scr[kk * 33 + 4 * q + 3] = x[3]; }
;     }
;     asm volatile("s_waitcnt lgkmcnt(0)" ::: "memory");
;     const int c = lane & 7;
; #pragma unroll
;     for (int j = 0; j < 4; ++j) { const int n = (lane >> 3) + 8 * j; const LAS float* s = scr + (8 * c) * 33 + n;
;         v4u o; o.x = pk2(s[0 * 33], s[1 * 33]); o.y = pk2(s[2 * 33], s[3 * 33]); o.z = pk2(s[4 * 33], s[5 * 33]); o.w = pk2(s[6 * 33], s[7 * 33]);
;         *(v4u*)(WT + (size_t)(n0 + n) * K + k0 + 8 * c) = o; }
;     asm volatile("s_waitcnt lgkmcnt(0)" ::: "memory");
	v_pk_mul_f32 v[16:17], v[16:17], v[18:19] op_sel_hi:[1,0]
	v_pk_mul_f32 v[14:15], v[14:15], v[18:19] op_sel_hi:[1,0]
	v_add_u32_e32 v18, 0x1080, v42
	ds_write2_b32 v18, v14, v15 offset1:1
	v_add_u32_e32 v14, 0x1088, v42
	ds_write2_b32 v14, v16, v17 offset1:1
	v_or_b32_e32 v14, s2, v38
	v_ashrrev_i32_e32 v15, 31, v14
	v_lshl_add_u64 v[14:15], v[14:15], 2, s[8:9]
	global_load_dword v14, v[14:15], off
	s_waitcnt vmcnt(0)
	v_pk_mul_f32 v[12:13], v[12:13], v[14:15] op_sel_hi:[1,0]
	v_pk_mul_f32 v[10:11], v[10:11], v[14:15] op_sel_hi:[1,0]
	v_add_u32_e32 v14, 0x14a0, v42
	ds_write2_b32 v14, v10, v11 offset1:1
	v_add_u32_e32 v10, 0x14a8, v42
	ds_write2_b32 v10, v12, v13 offset1:1
	v_or_b32_e32 v10, s2, v39
	v_ashrrev_i32_e32 v11, 31, v10
	v_lshl_add_u64 v[10:11], v[10:11], 2, s[8:9]
	global_load_dword v10, v[10:11], off
	s_waitcnt vmcnt(0)
	v_pk_mul_f32 v[8:9], v[8:9], v[10:11] op_sel_hi:[1,0]
	v_pk_mul_f32 v[6:7], v[6:7], v[10:11] op_sel_hi:[1,0]
	v_add_u32_e32 v10, 0x18c0, v42
	ds_write2_b32 v10, v6, v7 offset1:1
	v_add_u32_e32 v6, 0x18c8, v42
	ds_write2_b32 v6, v8, v9 offset1:1
	v_or_b32_e32 v6, s2, v40
	v_ashrrev_i32_e32 v7, 31, v6
	v_lshl_add_u64 v[6:7], v[6:7], 2, s[8:9]
	global_load_dword v6, v[6:7], off
	s_waitcnt vmcnt(0)
	v_pk_mul_f32 v[4:5], v[4:5], v[6:7] op_sel_hi:[1,0]
	v_pk_mul_f32 v[2:3], v[2:3], v[6:7] op_sel_hi:[1,0]
	v_add_u32_e32 v6, 0x1ce0, v42
	ds_write2_b32 v6, v2, v3 offset1:1
	v_add_u32_e32 v2, 0x1ce8, v42
	ds_write2_b32 v2, v4, v5 offset1:1
	s_waitcnt lgkmcnt(0)
	ds_read2_b32 v[8:9], v41 offset0:33 offset1:41
	ds_read2_b32 v[10:11], v41 offset1:8
	ds_read2_b32 v[12:13], v41 offset0:66 offset1:74
	ds_read2_b32 v[14:15], v41 offset0:99 offset1:107
	ds_read2_b32 v[16:17], v41 offset0:132 offset1:140
	ds_read2_b32 v[18:19], v41 offset0:165 offset1:173
	ds_read2_b32 v[20:21], v41 offset0:198 offset1:206
	ds_read2_b32 v[22:23], v41 offset0:231 offset1:239
	v_lshl_add_u64 v[6:7], s[2:3], 1, v[28:29]
	s_waitcnt lgkmcnt(6)
	v_cvt_pk_bf16_f32 v2, v10, v8
	s_waitcnt lgkmcnt(4)
	v_cvt_pk_bf16_f32 v3, v12, v14
	s_waitcnt lgkmcnt(2)
	v_cvt_pk_bf16_f32 v4, v16, v18
	s_waitcnt lgkmcnt(0)
	v_cvt_pk_bf16_f32 v5, v20, v22
	v_lshl_add_u64 v[30:31], v[6:7], 0, v[30:31]
	v_add_u32_e32 v8, 8, v24
	global_store_dwordx4 v[30:31], v[2:5], off
	v_add_u32_e32 v30, 16, v24
	v_ashrrev_i32_e32 v31, 31, v30
	v_cvt_pk_bf16_f32 v2, v11, v9
	v_ashrrev_i32_e32 v9, 31, v8
	v_lshlrev_b64 v[8:9], 11, v[8:9]
	v_cvt_pk_bf16_f32 v3, v13, v15
	v_cvt_pk_bf16_f32 v4, v17, v19
	v_cvt_pk_bf16_f32 v5, v21, v23
	v_lshl_add_u64 v[8:9], v[6:7], 0, v[8:9]
	global_store_dwordx4 v[8:9], v[2:5], off
	ds_read2_b32 v[8:9], v41 offset0:49 offset1:57
	ds_read2_b32 v[10:11], v41 offset0:16 offset1:24
	ds_read2_b32 v[12:13], v41 offset0:82 offset1:90
	ds_read2_b32 v[14:15], v41 offset0:115 offset1:123
	ds_read2_b32 v[16:17], v41 offset0:148 offset1:156
	ds_read2_b32 v[18:19], v41 offset0:181 offset1:189
	ds_read2_b32 v[20:21], v41 offset0:214 offset1:222
	ds_read2_b32 v[22:23], v41 offset0:247 offset1:255
	v_lshlrev_b64 v[30:31], 11, v[30:31]
	s_waitcnt lgkmcnt(6)
	v_cvt_pk_bf16_f32 v2, v10, v8
	s_waitcnt lgkmcnt(4)
	v_cvt_pk_bf16_f32 v3, v12, v14
	s_waitcnt lgkmcnt(2)
	v_cvt_pk_bf16_f32 v4, v16, v18
	s_waitcnt lgkmcnt(0)
	v_cvt_pk_bf16_f32 v5, v20, v22
	v_lshl_add_u64 v[30:31], v[6:7], 0, v[30:31]
	v_add_u32_e32 v8, 24, v24
	global_store_dwordx4 v[30:31], v[2:5], off
	s_nop 1
	v_cvt_pk_bf16_f32 v2, v11, v9
	v_ashrrev_i32_e32 v9, 31, v8
	v_lshlrev_b64 v[8:9], 11, v[8:9]
	v_cvt_pk_bf16_f32 v3, v13, v15
	v_cvt_pk_bf16_f32 v4, v17, v19
	v_cvt_pk_bf16_f32 v5, v21, v23
	v_lshl_add_u64 v[6:7], v[6:7], 0, v[8:9]
	global_store_dwordx4 v[6:7], v[2:5], off
	s_waitcnt lgkmcnt(0)
	s_cbranch_scc1 .LBB0_1278
